# head trim with byte-layout compensation (4 nops in the first QK MFMA shadow)
# speedup vs baseline: 1.0084x; 1.0084x over previous
.LBB0_407:
	v_mbcnt_lo_u32_b32 v128, -1, 0
	v_mbcnt_hi_u32_b32 v128, -1, v128
	s_add_i32 s7, s7, 0
	v_bfe_u32 v129, v128, 2, 2
	v_lshrrev_b32_e32 v130, 3, v128
	v_bfe_u32 v132, v128, 1, 1
	v_and_or_b32 v131, v130, s64, v129
	v_and_or_b32 v130, v130, 2, v132
	v_lshlrev_b32_e32 v133, 3, v128
	v_lshlrev_b32_e32 v131, 8, v131
	v_lshlrev_b32_e32 v130, 4, v130
	v_and_b32_e32 v133, 8, v133
	v_or3_b32 v160, v130, v131, v133
	v_lshlrev_b32_e32 v162, 6, v129
	v_or_b32_e32 v163, v160, v162
	v_ashrrev_i32_e32 v129, 5, v128
	v_lshlrev_b32_e32 v130, 7, v128
	v_lshrrev_b32_e32 v133, 1, v128
	v_and_b32_e32 v132, 0xf80, v130
	v_bitop3_b32 v128, v133, v129, 7 bitop3:0x6c
	v_lshl_add_u32 v134, v128, 4, v132
	v_add_u32_e32 v128, 2, v129
	v_bitop3_b32 v128, v128, v133, 7 bitop3:0x78
	v_lshl_add_u32 v136, v128, 4, v132
	v_add_u32_e32 v128, 4, v129
	v_bitop3_b32 v128, v128, v133, 7 bitop3:0x78
	v_add_u32_e32 v207, s7, v134
	v_lshl_add_u32 v168, v128, 4, v132
	v_add_u32_e32 v135, 6, v129
	ds_read_b128 v[128:131], v207
	v_bitop3_b32 v133, v135, v133, 7 bitop3:0x78
	v_add_u32_e32 v224, s48, v134
	v_add_u32_e32 v225, s7, v136
	v_lshl_add_u32 v169, v133, 4, v132
	ds_read_b128 v[132:135], v224
	v_add_u32_e32 v226, s48, v136
	ds_read_b128 v[136:139], v225
	ds_read_b128 v[140:143], v226
	v_bitop3_b32 v203, v160, s37, v162 bitop3:0x36
	v_bitop3_b32 v206, v160, s41, v162 bitop3:0x36
	s_waitcnt lgkmcnt(2)
	v_mfma_f32_32x32x16_bf16 v[144:159], v[128:131], v[132:135], 0
	s_nop 0
	s_nop 0
	s_nop 0
	s_nop 0
	v_add_u32_e32 v227, s7, v168
	v_add_u32_e32 v228, s48, v168
	ds_read_b128 v[128:131], v227
	ds_read_b128 v[132:135], v228
	s_waitcnt lgkmcnt(2)
	v_mfma_f32_32x32x16_bf16 v[144:159], v[136:139], v[140:143], v[144:159]
	v_add_u32_e32 v230, s7, v169
	v_add_u32_e32 v232, s48, v169
	ds_read_b128 v[136:139], v230
	ds_read_b128 v[140:143], v232
	s_waitcnt lgkmcnt(2)
	v_mfma_f32_32x32x16_bf16 v[144:159], v[128:131], v[132:135], v[144:159]
	ds_read_b128 v[128:131], v207 offset:8192
	ds_read_b128 v[132:135], v224 offset:4096
	s_waitcnt lgkmcnt(2)
	v_mfma_f32_32x32x16_bf16 v[144:159], v[136:139], v[140:143], v[144:159]
	ds_read_b128 v[178:181], v225 offset:8192
	ds_read_b128 v[182:185], v226 offset:4096
	s_waitcnt lgkmcnt(2)
	v_mfma_f32_32x32x16_bf16 v[128:143], v[128:131], v[132:135], 0
	s_nop 7
	v_exp_f32_e32 v173, v144
	v_exp_f32_e32 v169, v145
	v_exp_f32_e32 v177, v146
	v_exp_f32_e32 v171, v147
	ds_read_b128 v[144:147], v227 offset:8192
	ds_read_b128 v[190:193], v228 offset:4096
	s_waitcnt lgkmcnt(2)
	v_mfma_f32_32x32x16_bf16 v[128:143], v[178:181], v[182:185], v[128:143]
	v_exp_f32_e32 v183, v148
	v_exp_f32_e32 v175, v149
	v_exp_f32_e32 v189, v150
	v_exp_f32_e32 v179, v151
	ds_read_b128 v[148:151], v230 offset:8192
	ds_read_b128 v[196:199], v232 offset:4096
	s_waitcnt lgkmcnt(2)
	v_mfma_f32_32x32x16_bf16 v[128:143], v[144:147], v[190:193], v[128:143]
	v_exp_f32_e32 v193, v152
	v_exp_f32_e32 v181, v153
	v_exp_f32_e32 v195, v154
	v_exp_f32_e32 v187, v155
	s_waitcnt lgkmcnt(0)
	v_mfma_f32_32x32x16_bf16 v[128:143], v[148:151], v[196:199], v[128:143]
	v_exp_f32_e32 v197, v156
	v_exp_f32_e32 v185, v157
	v_exp_f32_e32 v199, v158
	v_exp_f32_e32 v191, v159
	s_cmp_eq_u32 s4, 0x3f0000
	s_cbranch_scc1 .Lattn_nodma_a
	v_mov_b32_e32 v213, 0
	v_add_u32_e32 v212, s4, v202
	s_xor_b32 s8, s7, 0x4000
	v_lshl_add_u64 v[208:209], v[212:213], 1, s[66:67]
	s_add_i32 s9, s49, s8
	s_mov_b32 s10, m0
	s_mov_b32 m0, s9
	s_nop 0
	global_load_lds_dwordx4 v[208:209], off
	s_mov_b32 m0, s10
	v_add_u32_e32 v210, s4, v201
	v_lshl_add_u64 v[208:209], v[208:209], 0, s[38:39]
	s_add_i32 s9, s33, s8
	s_mov_b32 s10, m0
	s_mov_b32 m0, s9
	s_nop 0
	global_load_lds_dwordx4 v[208:209], off
	s_mov_b32 m0, s10
	v_add_u32_e32 v212, 0x10000, v210
	v_lshl_add_u64 v[208:209], v[212:213], 1, s[68:69]
	s_add_i32 s9, s54, s8
	s_mov_b32 s10, m0
	s_mov_b32 m0, s9
	s_nop 0
	global_load_lds_dwordx4 v[208:209], off
	s_mov_b32 m0, s10
	v_add_u32_e32 v212, 0x18000, v210
	v_lshl_add_u64 v[208:209], v[212:213], 1, s[68:69]
	s_add_i32 s8, s47, s8
	s_mov_b32 s9, m0
	s_mov_b32 m0, s8
	s_nop 0
	global_load_lds_dwordx4 v[208:209], off
	s_mov_b32 m0, s9
